# diff attention loop: lane^16/^32 max via v_permlane swaps instead of ds_bpermute; packed f32 fma split into scalar fma
# speedup vs baseline: 1.0640x; 1.0175x over previous
.LBB0_1621:
	s_mov_b32 s5, s73
	s_add_i32 s5, s5, 4
	s_min_u32 s5, s5, s50
	v_mad_u64_u32 v[2:3], s[6:7], s5, v144, v[112:113]
	s_lshl_b32 s10, s5, 6
	s_and_b32 s5, s72, 0x18000
	s_add_i32 s5, s5, s51
	s_mov_b32 s6, m0
	s_mov_b32 m0, s5
	s_nop 0
	global_load_lds_dwordx4 v[2:3], off
	s_mov_b32 m0, s6
	v_lshl_add_u64 v[2:3], v[2:3], 0, s[78:79]
	s_add_i32 s6, s5, 0x2000
	s_mov_b32 s7, m0
	s_mov_b32 m0, s6
	s_nop 0
	global_load_lds_dwordx4 v[2:3], off
	s_mov_b32 m0, s7
	v_lshl_add_u64 v[92:93], s[10:11], 1, v[114:115]
	s_add_i32 s6, s5, 0x4000
	s_mov_b32 s7, m0
	s_mov_b32 m0, s6
	s_nop 0
	global_load_lds_dwordx4 v[92:93], off
	s_mov_b32 m0, s7
	s_mov_b32 s47, s11
	v_lshl_add_u64 v[2:3], v[92:93], 0, s[46:47]
	s_addk_i32 s5, 0x6000
	s_mov_b32 s6, m0
	s_mov_b32 m0, s5
	s_nop 0
	global_load_lds_dwordx4 v[2:3], off
	s_mov_b32 m0, s6
	s_add_i32 s73, s73, 1
	v_cmp_lt_u32_e32 vcc, s73, v109
	s_and_saveexec_b64 s[48:49], vcc
	s_cbranch_execz .LBB0_1620
	s_add_i32 s5, s72, 0xfffe8000
	s_and_b32 s5, s5, 0x18000
	s_add_i32 s5, s5, 0
	v_add_u32_e32 v2, s5, v152
	v_add_u32_e32 v3, v2, v155
	v_add_u32_e32 v117, v2, v156
	ds_read_b128 v[92:95], v3
	ds_read_b128 v[96:99], v3 offset:4096
	ds_read_b128 v[100:103], v117
	ds_read_b128 v[104:107], v117 offset:4096
	s_waitcnt lgkmcnt(3)
	v_mfma_f32_16x16x32_bf16 v[92:95], v[92:95], v[4:7], 0
	s_waitcnt lgkmcnt(2)
	v_mfma_f32_16x16x32_bf16 v[96:99], v[96:99], v[4:7], 0
	s_waitcnt lgkmcnt(1)
	v_mfma_f32_16x16x32_bf16 v[92:95], v[100:103], v[8:11], v[92:95]
	s_waitcnt lgkmcnt(0)
	v_mfma_f32_16x16x32_bf16 v[96:99], v[104:107], v[8:11], v[96:99]
	ds_read_b128 v[100:103], v3 offset:8192
	ds_read_b128 v[104:107], v3 offset:12288
	ds_read_b128 v[118:121], v117 offset:8192
	ds_read_b128 v[122:125], v117 offset:12288
	v_add_u32_e32 v3, v2, v157
	s_waitcnt lgkmcnt(3)
	v_mfma_f32_16x16x32_bf16 v[100:103], v[100:103], v[4:7], 0
	v_add_u32_e32 v2, v2, v158
	v_fma_f32 v126, v94, s24, -v0
	v_fma_f32 v127, v95, s24, -v0
	v_fma_f32 v130, v98, s24, -v0
	v_fma_f32 v131, v99, s24, -v0
	s_waitcnt lgkmcnt(2)
	v_mfma_f32_16x16x32_bf16 v[104:107], v[104:107], v[4:7], 0
	v_fma_f32 v128, v96, s24, -v0
	v_fma_f32 v129, v97, s24, -v0
	s_waitcnt lgkmcnt(1)
	v_mfma_f32_16x16x32_bf16 v[100:103], v[118:121], v[8:11], v[100:103]
	ds_read_b128 v[118:121], v3
	ds_read_b128 v[132:135], v3 offset:4096
	ds_read_b128 v[136:139], v2
	ds_read_b128 v[162:165], v2 offset:4096
	ds_read_b128 v[166:169], v3 offset:8192
	ds_read_b128 v[170:173], v3 offset:12288
	ds_read_b128 v[174:177], v2 offset:8192
	ds_read_b128 v[178:181], v2 offset:12288
	s_waitcnt lgkmcnt(8)
	v_mfma_f32_16x16x32_bf16 v[104:107], v[122:125], v[8:11], v[104:107]
	v_fma_f32 v124, v92, s24, -v0
	v_fma_f32 v125, v93, s24, -v0
	v_fma_f32 v122, v102, s24, -v0
	v_fma_f32 v123, v103, s24, -v0
	s_waitcnt lgkmcnt(7)
	v_mfma_f32_16x16x32_bf16 v[92:95], v[118:121], v[12:15], 0
	v_fma_f32 v118, v100, s24, -v0
	v_fma_f32 v119, v101, s24, -v0
	s_nop 0
	v_fma_f32 v2, v106, s24, -v0
	v_fma_f32 v3, v107, s24, -v0
	v_max_f32_e32 v100, v126, v127
	v_max_f32_e32 v101, v130, v131
	v_fma_f32 v120, v104, s24, -v0
	v_fma_f32 v121, v105, s24, -v0
	v_max3_f32 v100, v124, v125, v100
	v_max3_f32 v101, v128, v129, v101
	v_max_f32_e32 v105, v122, v123
	v_max_f32_e32 v106, v2, v3
	v_max3_f32 v104, v100, s25, v101
	v_max3_f32 v105, v118, v119, v105
	v_max3_f32 v106, v120, v121, v106
	v_max3_f32 v117, v104, v105, v106
	v_mov_b32_e32 v104, v117
	s_waitcnt lgkmcnt(6)
	v_mfma_f32_16x16x32_bf16 v[96:99], v[132:135], v[12:15], 0
	v_permlane16_swap_b32_e32 v104, v117
	s_waitcnt lgkmcnt(0)
	v_max_f32_e32 v117, v117, v104
	v_mfma_f32_16x16x32_bf16 v[100:103], v[166:169], v[12:15], 0
	v_mov_b32_e32 v132, v117
	s_nop 1
	v_permlane32_swap_b32_e32 v132, v117
	v_mfma_f32_16x16x32_bf16 v[104:107], v[170:173], v[12:15], 0
	v_max_f32_e32 v117, v117, v132
	v_cmp_lt_f32_e32 vcc, s70, v117
	v_mfma_f32_16x16x32_bf16 v[92:95], v[136:139], v[16:19], v[92:95]
	v_mfma_f32_16x16x32_bf16 v[96:99], v[162:165], v[16:19], v[96:99]
	v_mfma_f32_16x16x32_bf16 v[100:103], v[174:177], v[16:19], v[100:103]
	v_mfma_f32_16x16x32_bf16 v[104:107], v[178:181], v[16:19], v[104:107]
	s_cbranch_vccz .LBB0_1624
	v_max_f32_e32 v117, v117, v117
	v_max_f32_e32 v117, 0, v117
	v_exp_f32_e64 v132, -v117
	v_add_f32_e32 v0, v0, v117
	v_sub_f32_e32 v124, v124, v117
	v_sub_f32_e32 v125, v125, v117
	v_pk_mul_f32 v[86:87], v[86:87], v[132:133] op_sel_hi:[1,0]
	v_pk_mul_f32 v[84:85], v[84:85], v[132:133] op_sel_hi:[1,0]
	v_pk_mul_f32 v[26:27], v[26:27], v[132:133] op_sel_hi:[1,0]
	v_pk_mul_f32 v[24:25], v[24:25], v[132:133] op_sel_hi:[1,0]
	v_pk_mul_f32 v[34:35], v[34:35], v[132:133] op_sel_hi:[1,0]
	v_pk_mul_f32 v[32:33], v[32:33], v[132:133] op_sel_hi:[1,0]
	v_pk_mul_f32 v[38:39], v[38:39], v[132:133] op_sel_hi:[1,0]
	v_pk_mul_f32 v[36:37], v[36:37], v[132:133] op_sel_hi:[1,0]
	v_pk_mul_f32 v[46:47], v[46:47], v[132:133] op_sel_hi:[1,0]
	v_pk_mul_f32 v[44:45], v[44:45], v[132:133] op_sel_hi:[1,0]
	v_pk_mul_f32 v[54:55], v[54:55], v[132:133] op_sel_hi:[1,0]
	v_pk_mul_f32 v[52:53], v[52:53], v[132:133] op_sel_hi:[1,0]
	v_pk_mul_f32 v[62:63], v[62:63], v[132:133] op_sel_hi:[1,0]
	v_pk_mul_f32 v[60:61], v[60:61], v[132:133] op_sel_hi:[1,0]
	v_pk_mul_f32 v[70:71], v[70:71], v[132:133] op_sel_hi:[1,0]
	v_pk_mul_f32 v[68:69], v[68:69], v[132:133] op_sel_hi:[1,0]
	v_pk_mul_f32 v[90:91], v[90:91], v[132:133] op_sel_hi:[1,0]
	v_pk_mul_f32 v[88:89], v[88:89], v[132:133] op_sel_hi:[1,0]
	v_sub_f32_e32 v126, v126, v117
	v_sub_f32_e32 v127, v127, v117
	v_sub_f32_e32 v128, v128, v117
	v_sub_f32_e32 v129, v129, v117
	v_sub_f32_e32 v130, v130, v117
	v_sub_f32_e32 v131, v131, v117
	v_sub_f32_e32 v118, v118, v117
	v_sub_f32_e32 v119, v119, v117
	v_sub_f32_e32 v122, v122, v117
	v_sub_f32_e32 v123, v123, v117
	v_sub_f32_e32 v120, v120, v117
	v_sub_f32_e32 v121, v121, v117
	v_sub_f32_e32 v2, v2, v117
	v_sub_f32_e32 v3, v3, v117
.LBB0_1624:
	s_nop 3
	v_fma_f32 v138, v94, s24, -v116
	v_fma_f32 v139, v95, s24, -v116
	v_fma_f32 v132, v98, s24, -v116
	v_fma_f32 v133, v99, s24, -v116
	v_fma_f32 v136, v92, s24, -v116
	v_fma_f32 v137, v93, s24, -v116
	v_fma_f32 v134, v96, s24, -v116
	v_fma_f32 v135, v97, s24, -v116
	v_fma_f32 v96, v100, s24, -v116
	v_fma_f32 v97, v101, s24, -v116
	v_max_f32_e32 v100, v138, v139
	v_max_f32_e32 v101, v132, v133
	v_fma_f32 v98, v102, s24, -v116
	v_fma_f32 v99, v103, s24, -v116
	v_fma_f32 v92, v106, s24, -v116
	v_fma_f32 v93, v107, s24, -v116
	v_max3_f32 v100, v136, v137, v100
	v_max3_f32 v101, v134, v135, v101
	v_fma_f32 v94, v104, s24, -v116
	v_fma_f32 v95, v105, s24, -v116
	v_max3_f32 v100, v100, s25, v101
	v_max_f32_e32 v101, v98, v99
	v_max_f32_e32 v102, v92, v93
	v_max3_f32 v101, v96, v97, v101
	v_max3_f32 v102, v94, v95, v102
	v_max3_f32 v100, v100, v101, v102
	v_mov_b32_e32 v101, v100
	s_nop 1
	v_permlane16_swap_b32_e32 v101, v100
	v_max_f32_e32 v100, v100, v101
	v_mov_b32_e32 v101, v100
	s_nop 1
	v_permlane32_swap_b32_e32 v101, v100
	v_max_f32_e32 v100, v100, v101
	v_cmp_lt_f32_e32 vcc, s70, v100
	s_cbranch_vccz .LBB0_1619
	v_max_f32_e32 v100, v100, v100
	v_max_f32_e32 v101, 0, v100
	v_exp_f32_e64 v100, -v101
	v_add_f32_e32 v116, v116, v101
	v_sub_f32_e32 v136, v136, v101
	v_sub_f32_e32 v137, v137, v101
	v_pk_mul_f32 v[82:83], v[82:83], v[100:101] op_sel_hi:[1,0]
	v_pk_mul_f32 v[80:81], v[80:81], v[100:101] op_sel_hi:[1,0]
	v_pk_mul_f32 v[22:23], v[22:23], v[100:101] op_sel_hi:[1,0]
	v_pk_mul_f32 v[20:21], v[20:21], v[100:101] op_sel_hi:[1,0]
	v_pk_mul_f32 v[30:31], v[30:31], v[100:101] op_sel_hi:[1,0]
	v_pk_mul_f32 v[28:29], v[28:29], v[100:101] op_sel_hi:[1,0]
	v_pk_mul_f32 v[42:43], v[42:43], v[100:101] op_sel_hi:[1,0]
	v_pk_mul_f32 v[40:41], v[40:41], v[100:101] op_sel_hi:[1,0]
	v_pk_mul_f32 v[50:51], v[50:51], v[100:101] op_sel_hi:[1,0]
	v_pk_mul_f32 v[48:49], v[48:49], v[100:101] op_sel_hi:[1,0]
	v_pk_mul_f32 v[58:59], v[58:59], v[100:101] op_sel_hi:[1,0]
	v_pk_mul_f32 v[56:57], v[56:57], v[100:101] op_sel_hi:[1,0]
	v_pk_mul_f32 v[66:67], v[66:67], v[100:101] op_sel_hi:[1,0]
	v_pk_mul_f32 v[64:65], v[64:65], v[100:101] op_sel_hi:[1,0]
	v_pk_mul_f32 v[74:75], v[74:75], v[100:101] op_sel_hi:[1,0]
	v_pk_mul_f32 v[72:73], v[72:73], v[100:101] op_sel_hi:[1,0]
	v_pk_mul_f32 v[78:79], v[78:79], v[100:101] op_sel_hi:[1,0]
	v_pk_mul_f32 v[76:77], v[76:77], v[100:101] op_sel_hi:[1,0]
	v_sub_f32_e32 v138, v138, v101
	v_sub_f32_e32 v139, v139, v101
	v_sub_f32_e32 v134, v134, v101
	v_sub_f32_e32 v135, v135, v101
	v_sub_f32_e32 v132, v132, v101
	v_sub_f32_e32 v133, v133, v101
	v_sub_f32_e32 v96, v96, v101
	v_sub_f32_e32 v97, v97, v101
	v_sub_f32_e32 v98, v98, v101
	v_sub_f32_e32 v99, v99, v101
	v_sub_f32_e32 v94, v94, v101
	v_sub_f32_e32 v95, v95, v101
	v_sub_f32_e32 v92, v92, v101
	v_sub_f32_e32 v93, v93, v101
	s_branch .LBB0_1619
